# on top of v43: the same chunk-pair swizzle extended to the QH/QM/KM tiles (writer row bases and fragment readers): all ~70 MFMA fragment reads per chunk of the HGRN2 output phase are now bank-conflict
# baseline (speedup 1.0000x reference)
; #define LAS __attribute__((address_space(3)))
; #define GAS __attribute__((address_space(1)))
; #define ARGP(i) ((const GAS float*)ldptr(ptab, (i)))
; __device__ __forceinline__ Ctx load_ctx(LAS unsigned long long* ptab) {
;     Ctx c; const int step = (int)ldptr(ptab, 16); c.NG = (int)ldptr(ptab, 15); c.layer = step / c.NG; c.g = step - c.layer * c.NG; c.TOKG = NTOK / c.NG; c.j = c.layer >> 1; c.even = !(c.layer & 1);
;     int tid_raw = threadIdx.x; asm volatile("" : "+v"(tid_raw)); c.tid = tid_raw; c.lane = c.tid & 63; c.wave = __builtin_amdgcn_readfirstlane(c.tid >> 6);
;     c.G = gridDim.x; c.bid = blockIdx.x; c.gw = c.bid * 8 + c.wave; c.ngw = c.G * 8;
;     c.wsb = (GAS unsigned char*)ldptr(ptab, 14);
;     c.Wt_in = (GAS bf16*)(c.wsb + WS_WIN); c.Wt_out = (GAS bf16*)(c.wsb + WS_WOUT); c.lbtab = (GAS float*)(c.wsb + WS_MISC); c.proj = (GAS bf16*)(c.wsb + WS_PROJ);
;     c.ybuf = (GAS bf16*)(c.wsb + WS_PROJ + (size_t)c.TOKG * (PW * 2)); c.xn = (GAS bf16*)(c.wsb + WS_PROJ + (size_t)c.TOKG * (PW * 2 + MW * 2));
;     c.xres = (GAS bf16*)(c.wsb + WS_PROJ + (size_t)c.TOKG * (PW * 2 + MW * 2 + AUX_PER_TOK)); c.ssq = (GAS float*)(c.wsb + WS_SSQ);
;     c.row0 = (size_t)c.g * c.TOKG; return c;
; __global__ void __launch_bounds__(512, 2) fwd(Args a) {
;     ...
;             const Ctx c = load_ctx(ptab);
;             if (__builtin_amdgcn_readfirstlane(c.tid) >= 256) __builtin_amdgcn_s_setprio(1);
;             if (c.even) merge_conv(c.proj, c.xn, (const GAS float*)(c.xn + (size_t)c.TOKG * 3072), c.ybuf, c.TOKG, ARGP(3) + c.j * 3 * 1024, c.lane, c.gw, c.ngw);
;             else hgrn_r3(c.proj, (const GAS float*)c.xn, (const GAS float*)(c.wsb + WS_RD), c.ybuf, c.TOKG, ARGP(11) + c.j * MW, lds, c.tid, c.lane, c.wave, c.bid, c.G);
.LBB0_374:
	s_abs_i32 s5, s4
	v_cvt_f32_u32_e32 v0, s5
	s_sub_i32 s8, 0, s5
	s_ashr_i32 s7, s3, 31
	s_abs_i32 s3, s3
	v_rcp_iflag_f32_e32 v0, v0
	s_ashr_i32 s4, s4, 31
	s_xor_b32 s7, s7, s4
	v_and_b32_e32 v99, 63, v98
	v_mul_f32_e32 v0, 0x4f7ffffe, v0
	v_cvt_u32_f32_e32 v0, v0
	s_nop 0
	v_readfirstlane_b32 s9, v0
	s_mul_i32 s8, s8, s9
	s_mul_hi_u32 s8, s9, s8
	s_add_i32 s9, s9, s8
	s_mul_hi_u32 s8, s3, s9
	s_mul_i32 s10, s8, s5
	s_sub_i32 s3, s3, s10
	s_add_i32 s11, s8, 1
	s_sub_i32 s10, s3, s5
	s_cmp_ge_u32 s3, s5
	s_cselect_b32 s8, s11, s8
	s_cselect_b32 s3, s10, s3
	s_add_i32 s10, s8, 1
	s_cmp_ge_u32 s3, s5
	s_cselect_b32 s3, s10, s8
	s_lshr_b32 s8, s9, 17
	s_xor_b32 s3, s3, s7
	s_mul_i32 s9, s8, s5
	s_sub_i32 s7, s3, s7
	s_sub_i32 s3, 0x8000, s9
	s_add_i32 s9, s8, 1
	s_sub_i32 s10, s3, s5
	s_cmp_ge_u32 s3, s5
	s_cselect_b32 s8, s9, s8
	s_cselect_b32 s3, s10, s3
	s_add_i32 s9, s8, 1
	s_cmp_ge_u32 s3, s5
	s_cselect_b32 s3, s9, s8
	s_xor_b32 s3, s3, s4
	s_sub_i32 s96, s3, s4
	s_ashr_i32 s97, s96, 31
	s_ashr_i32 s3, s7, 1
	s_ashr_i32 s40, s6, 6
	s_lshl_b64 s[98:99], s[96:97], 14
	s_bitcmp1_b32 s7, 0
	s_cselect_b64 s[8:9], -1, 0
	s_mov_b64 s[4:5], -1
	s_and_b64 vcc, exec, s[8:9]
	s_cbranch_vccz .LBB0_401
	v_readlane_b32 s4, v236, 30
	s_nop 1
	v_mov_b32_e32 v0, s4
	ds_read_b64 v[0:1], v0
	s_ashr_i32 s4, s96, 31
	s_lshr_b32 s4, s4, 19
	s_add_i32 s5, s96, s4
	s_ashr_i32 s5, s5, 13
	s_lshl_b32 s53, s5, 7
	s_waitcnt lgkmcnt(0)
	v_readfirstlane_b32 s4, v1
	s_cmp_ge_i32 s2, s53
	v_readfirstlane_b32 s5, v0
	s_cbranch_scc1 .LBB0_400
; #define GAS __attribute__((address_space(1)))
; __device__ __forceinline__ void hgrn_r3(const GAS bf16* proj, const GAS float* RU, const GAS float* RD, GAS bf16* y, int TOKG, const GAS float* ogain, unsigned char* lds, int tid, int lane, int wave, int bid, int G) {
;     ...
;     const int nruns = (TOKG / SEQ) * 16 * (128 / RUNC);
;     const int fr = lane & 15, fq = lane >> 4;
;     unsigned rq[8], rg[8], rv[8];
;     unsigned voff[8], zoff[4], yoff[4];
; #pragma unroll
;     for (int i = 0; i < 8; ++i) voff[i] = (unsigned)((wave * 8 + i) * (PW * 2) + lane * 4);
; #pragma unroll
;     for (int t2 = 0; t2 < 4; ++t2) { zoff[t2] = (unsigned)(((16 * t2 + fr) * PW + 16 * wave + 4 * fq) * 2); yoff[t2] = (unsigned)(((16 * t2 + fr) * MW + 16 * wave + 4 * fq) * 2); }
;     const __amdgpu_buffer_rsrc_t prs = __builtin_amdgcn_make_buffer_rsrc((void*)proj, 0, (int)((size_t)TOKG * PW * 2), 0x00020000);
;     ...
;     for (int run = bid; run < nruns; run += G) {
;         const int u0 = run * RUNC, seq = run / (128 / RUNC), rr = run - seq * (128 / RUNC), h = seq & 15, bl = seq >> 4;
;         H3_LOAD(u0);
;         const int v0 = 16 * wave + 4 * fq;
;         const f32x4 og = *(const GAS f32x4*)(ogain + h * 128 + v0);
	s_add_u32 s44, s0, 0x1800000
	s_addc_u32 s56, s1, 0
	s_lshl_b32 s46, s96, 14
	s_and_b32 s45, s56, 0xffff
	s_add_u32 s57, s44, s98
	s_addc_u32 s74, s56, s99
	s_lshl_b64 s[8:9], s[96:97], 12
	s_add_u32 s8, s57, s8
	s_addc_u32 s9, s74, s9
	s_lshl_b32 s10, s3, 11
	s_ashr_i32 s11, s10, 31
	s_lshl_b64 s[10:11], s[10:11], 2
	v_lshrrev_b32_e32 v2, 4, v99
	s_add_u32 s10, s5, s10
	v_lshlrev_b32_e32 v0, 2, v99
	v_lshlrev_b32_e32 v3, 2, v2
	s_addc_u32 s11, s4, s11
	s_lshl_b32 s75, s40, 4
	v_lshl_or_b32 v100, s40, 17, v0
	v_and_b32_e32 v4, 15, v98
	v_or_b32_e32 v0, s75, v3
	v_or_b32_e32 v1, 48, v4
	v_lshlrev_b32_e32 v5, 1, v0
	v_lshl_add_u32 v68, v1, 12, v5
	s_movk_i32 s4, 0x3000
	v_mad_u32_u24 v70, v1, s4, v68
	v_or_b32_e32 v1, 32, v4
	v_lshl_add_u32 v72, v1, 12, v5
	v_mad_u32_u24 v74, v1, s4, v72
	v_or_b32_e32 v1, 16, v4
	v_lshl_add_u32 v76, v1, 12, v5
	v_mad_u32_u24 v78, v1, s4, v76
	s_waitcnt vmcnt(0)
	v_lshl_add_u32 v80, v4, 12, v5
	v_ashrrev_i32_e32 v1, 31, v0
	v_or_b32_e32 v5, s75, v4
	v_lshl_add_u64 v[84:85], v[0:1], 2, s[10:11]
	v_lshlrev_b32_e32 v0, 7, v5
	v_mad_u32_u24 v82, v4, s4, v80
	s_lshl_b32 s4, s40, 2
	v_ashrrev_i32_e32 v1, 31, v0
	s_add_i32 s4, s4, 0
	v_lshl_add_u64 v[0:1], v[0:1], 2, s[8:9]
	v_and_b32_e32 v112, 48, v99
	s_add_i32 s42, s4, 0x14800
	v_lshl_add_u64 v[86:87], v[0:1], 0, v[112:113]
	v_lshl_add_u64 v[0:1], s[0:1], 0, v[112:113]
	s_mov_b64 s[4:5], 0x1410000
	s_movk_i32 s25, 0x110
	v_lshl_add_u64 v[88:89], v[0:1], 0, s[4:5]
	v_mul_lo_u32 v0, v5, s25
	v_readlane_b32 s4, v236, 31
	s_add_i32 s5, 0, 0x13800
	v_lshlrev_b32_e32 v1, 3, v99
	v_add_u32_e32 v108, s4, v0
	s_lshl_b32 s4, s40, 9
	s_add_i32 s4, s5, s4
	v_add_u32_e32 v116, s5, v1
	v_readlane_b32 s5, v236, 32
	s_movk_i32 s7, 0x120
	s_add_i32 s43, s5, s75
	v_add_u32_e32 v110, s4, v1
	v_mad_u32_u24 v111, v99, s7, 0
	s_movk_i32 s4, 0xfee4
	s_cmp_lt_u32 s6, 64
	v_mad_i32_i24 v6, v99, s4, v111
	s_cselect_b64 s[70:71], -1, 0
	s_ashr_i32 s22, s6, 7
	s_lshl_b32 s4, s40, 1
	v_mov_b32_e32 v7, s5
	s_and_b32 s23, s4, 2
	v_lshl_or_b32 v8, s22, 4, v4
	s_movk_i32 s4, 0x90
	v_and_b32_e32 v109, 48, v98
	v_mad_u32_u24 v7, v99, s7, v7
	v_mul_lo_u32 v9, v8, s4
	v_readlane_b32 s6, v236, 33
	v_readlane_b32 s7, v236, 34
	s_cmp_gt_i32 s40, 0
	v_add_u32_e32 v9, s6, v9
	v_add_u32_e32 v117, s7, v112
	v_add_u32_e32 v13, s6, v109
	v_add_u32_e32 v120, s7, v1
	s_cselect_b64 s[6:7], -1, 0
	s_cmp_gt_i32 s40, 1
	s_cselect_b64 s[8:9], -1, 0
	s_cmp_gt_i32 s40, 2
	s_cselect_b64 s[10:11], -1, 0
	s_cmp_gt_i32 s40, 3
	s_cselect_b64 s[12:13], -1, 0
	s_cmp_gt_i32 s40, 4
	s_cselect_b64 s[14:15], -1, 0
	s_cmp_gt_i32 s40, 5
	s_cselect_b64 s[16:17], -1, 0
	s_cmp_gt_i32 s40, 6
	v_and_b32_e32 v15, 64, v190
	s_cselect_b64 s[18:19], -1, 0
	s_cmp_gt_i32 s40, 7
	v_xor_b32_e32 v14, 16, v190
	v_add_u32_e32 v15, 64, v15
	s_cselect_b64 s[20:21], -1, 0
	s_cmp_le_i32 s23, s22
	v_cmp_lt_i32_e32 vcc, v14, v15
	s_cselect_b64 s[82:83], -1, 0
	s_lshl_b32 s24, s23, 4
	v_cndmask_b32_e32 v14, v190, v14, vcc
	s_cmp_lt_i32 s23, s22
	v_or_b32_e32 v18, s24, v3
	v_lshlrev_b32_e32 v118, 2, v14
	v_xor_b32_e32 v14, 32, v190
	s_cselect_b64 s[48:49], -1, 0
	s_or_b32 s30, s24, 16
	v_or_b32_e32 v19, 2, v18
	v_cmp_lt_i32_e32 vcc, v14, v15
	v_cmp_gt_i32_e64 s[26:27], v19, v8
	v_or_b32_e32 v19, 3, v18
	v_or_b32_e32 v3, s30, v3
	v_lshlrev_b32_e32 v0, 3, v2
	v_mul_lo_u32 v10, v8, s25
	v_mul_lo_u32 v5, v5, s4
	v_cndmask_b32_e32 v14, v190, v14, vcc
	v_lshlrev_b32_e32 v15, 5, v4
	v_or_b32_e32 v1, s24, v4
	v_or_b32_e32 v16, s30, v4
	v_cmp_gt_i32_e64 s[28:29], v19, v8
	v_or_b32_e32 v19, 2, v3
	v_mul_u32_u24_e32 v2, 0x120, v99
	v_add_u32_e32 v10, 0, v10
	v_add_u32_e32 v11, 0, v109
	v_add_u32_e32 v5, 0, v5
	v_add_u32_e32 v12, s5, v109
	v_lshlrev_b32_e32 v119, 2, v14
	v_lshlrev_b32_e32 v14, 5, v99
	s_mul_i32 s54, s40, 0x880
	v_mad_u32_u24 v1, v1, s25, 0
	v_mad_u32_u24 v16, v16, s25, 0
	v_mul_u32_u24_e32 v17, 0x110, v4
	v_mul_u32_u24_e32 v4, 0x90, v4
	v_cmp_gt_i32_e64 s[22:23], v18, v8
	v_cmp_lt_i32_e64 s[24:25], v18, v8
	v_lshlrev_b32_e32 v18, 1, v18
	v_cmp_gt_i32_e64 s[30:31], v3, v8
	v_cmp_lt_i32_e64 s[34:35], v3, v8
	v_cmp_gt_i32_e64 s[36:37], v19, v8
	v_or_b32_e32 v19, 3, v3
	v_lshlrev_b32_e32 v3, 1, v3
	v_add_u32_e32 v121, v108, v0
	v_add_u32_e32 v0, 0, v15
	v_or_b32_e32 v101, 0x4000, v100
	v_or_b32_e32 v102, 0x8000, v100
	v_or_b32_e32 v103, 0xc000, v100
	v_or_b32_e32 v104, 0x10000, v100
	v_or_b32_e32 v105, 0x14000, v100
	v_or_b32_e32 v106, 0x18000, v100
	v_or_b32_e32 v107, 0x1c000, v100
	v_cmp_gt_u32_e64 s[4:5], 16, v99
	v_mov_b32_e32 v83, v113
	v_mov_b32_e32 v79, v113
	v_mov_b32_e32 v75, v113
	v_mov_b32_e32 v71, v113
	v_mov_b32_e32 v81, v113
	v_mov_b32_e32 v77, v113
	v_mov_b32_e32 v73, v113
	v_mov_b32_e32 v69, v113
	v_cmp_gt_i32_e64 s[38:39], v19, v8
	v_add_u32_e32 v122, s54, v6
	v_add_u32_e32 v123, s75, v7
	v_add_u32_e32 v124, s43, v2
	v_add_u32_e32 v125, v1, v109
	v_add_u32_e32 v126, v9, v18
	v_add_u32_e32 v127, v16, v109
	v_add_u32_e32 v128, v9, v3
	v_add_u32_e32 v129, v11, v17
	v_add_u32_e32 v130, v5, v109
	v_add_u32_e32 v131, v12, v4
	v_add_u32_e32 v132, v13, v4
	v_add_u32_e32 v133, 0x14800, v0
	v_add_u32_e32 v134, v10, v109
	v_add_u32_e32 v135, s42, v14
	v_add_u32_e32 v213, 4, v99
	v_and_b32_e32 v213, 8, v213
	v_lshlrev_b32_e32 v213, 1, v213
	v_lshrrev_b32_e32 v234, 1, v99
	v_and_b32_e32 v234, 16, v234
	v_xor_b32_e32 v235, v234, v213
	v_sub_u32_e32 v235, v235, v234
	v_add_u32_e32 v126, v126, v235
	v_add_u32_e32 v128, v128, v235
	v_add_u32_e32 v121, v121, v235
	v_and_b32_e32 v234, 16, v99
	v_xor_b32_e32 v235, v234, v213
	v_sub_u32_e32 v213, v235, v234
	v_add_u32_e32 v130, v130, v213
	v_add_u32_e32 v131, v131, v213
	v_add_u32_e32 v132, v132, v213
	v_lshlrev_b32_e32 v234, 1, v99
	v_add_u32_e32 v234, 4, v234
	v_and_b32_e32 v234, 8, v234
	v_lshlrev_b32_e32 v234, 1, v234
	v_mov_b32_e32 v235, s75
	v_and_b32_e32 v235, 16, v235
	v_xor_b32_e32 v234, v234, v235
	v_sub_u32_e32 v234, v234, v235
	v_add_u32_e32 v123, v123, v234
	v_add_u32_e32 v124, v124, v234
	v_add_u32_e32 v111, v111, v234
	v_mov_b32_e32 v234, s75
	v_and_b32_e32 v234, 16, v234
	v_xor_b32_e32 v122, v122, v234
	v_add_u32_e32 v129, v129, v213
	v_add_u32_e32 v125, v125, v213
	v_add_u32_e32 v127, v127, v213
	v_add_u32_e32 v134, v134, v213
	v_readlane_b32 s76, v236, 18
	v_readlane_b32 s68, v236, 17
	v_readlane_b32 s87, v236, 16
	v_readlane_b32 s94, v236, 15
	s_mov_b32 s97, s2
	s_branch .LBB0_378

; #define LAS __attribute__((address_space(3)))
; __device__ __forceinline__ float lo16(unsigned w) { return __uint_as_float(w << 16); }
; __device__ __forceinline__ void hgrn_r3(const GAS bf16* proj, const GAS float* RU, const GAS float* RD, GAS bf16* y, int TOKG, const GAS float* ogain, unsigned char* lds, int tid, int lane, int wave, int bid, int G) {
;     ...
;             float f0[8], f1[8], qv0[8], qv1[8]; float run0 = 0.f, run1 = 0.f; v4u vv0, vv1;
;             { float p0 = 1.f, p1 = 1.f;
; #pragma unroll
;               for (int i = 0; i < 8; ++i) { const float g0 = lo16(rg[i]), g1 = hi16(rg[i]); run0 += g0; run1 += g1; f0[i] = __builtin_amdgcn_exp2f(g0); f1[i] = __builtin_amdgcn_exp2f(g1);
;                   p0 *= f0[i]; p1 *= f1[i]; qv0[i] = lo16(rq[i]) * p0; qv1[i] = hi16(rq[i]) * p1; } }
;             vv0.x = (rv[0] & 0xffffu) | (rv[1] << 16); vv0.y = (rv[2] & 0xffffu) | (rv[3] << 16); vv0.z = (rv[4] & 0xffffu) | (rv[5] << 16); vv0.w = (rv[6] & 0xffffu) | (rv[7] << 16);
;             vv1.x = (rv[0] >> 16) | (rv[1] & 0xffff0000u); vv1.y = (rv[2] >> 16) | (rv[3] & 0xffff0000u); vv1.z = (rv[4] >> 16) | (rv[5] & 0xffff0000u); vv1.w = (rv[6] >> 16) | (rv[7] & 0xffff0000u);
;             if (ci + 1 < RUNC) H3_LOAD(u + 1);
;             *(LAS f32x2h*)(segtot + wave * 128 + 2 * lane) = (f32x2h){run0, run1};
;             *(LAS v4u*)(L + H3_VT + (2 * lane) * HS + wave * 16) = vv0; *(LAS v4u*)(L + H3_VT + (2 * lane + 1) * HS + wave * 16) = vv1;
;             __syncthreads();
;             { float pre0 = 0.f, pre1 = 0.f, gr0 = 0.f, gr1 = 0.f, tot0 = 0.f, tot1 = 0.f;
; #pragma unroll
;               for (int s8 = 0; s8 < 8; ++s8) { const f32x2h t = *(const LAS f32x2h*)(segtot + s8 * 128 + 2 * lane); tot0 += t.x; tot1 += t.y; pre0 += (s8 < wave) ? t.x : 0.f; pre1 += (s8 < wave) ? t.y : 0.f; if (s8 < 4) { gr0 += t.x; gr1 += t.y; } }
;               unsigned kw0[4], kw1[4];
;               const float eg0 = __builtin_amdgcn_exp2f(fminf(-gr0, 115.f)), eg1 = __builtin_amdgcn_exp2f(fminf(-gr1, 115.f)), tg0 = __builtin_amdgcn_exp2f(tot0 - gr0), tg1 = __builtin_amdgcn_exp2f(tot1 - gr1);
;               const float ep0 = __builtin_amdgcn_exp2f(pre0), ep1 = __builtin_amdgcn_exp2f(pre1);
;               float kv0[8], kv1[8], m0_ = __builtin_amdgcn_exp2f(fminf(gr0 - (pre0 + run0), 115.f)), m1_ = __builtin_amdgcn_exp2f(fminf(gr1 - (pre1 + run1), 115.f));
.LBB0_386:
	v_lshlrev_b32_e32 v166, 16, v163
	v_and_b32_e32 v167, 0xffff0000, v163
	v_lshlrev_b32_e32 v168, 16, v164
	v_and_b32_e32 v169, 0xffff0000, v164
	v_lshlrev_b32_e32 v164, 16, v161
	v_and_b32_e32 v165, 0xffff0000, v161
	v_lshlrev_b32_e32 v176, 16, v57
	v_and_b32_e32 v177, 0xffff0000, v57
	v_lshlrev_b32_e32 v182, 16, v56
	v_and_b32_e32 v183, 0xffff0000, v56
	v_pk_add_f32 v[56:57], v[166:167], 0 op_sel_hi:[1,0]
	v_lshlrev_b32_e32 v170, 16, v162
	v_and_b32_e32 v171, 0xffff0000, v162
	v_lshlrev_b32_e32 v162, 16, v61
	v_and_b32_e32 v163, 0xffff0000, v61
	v_lshlrev_b32_e32 v172, 16, v160
	v_and_b32_e32 v173, 0xffff0000, v160
	v_lshlrev_b32_e32 v160, 16, v59
	v_and_b32_e32 v161, 0xffff0000, v59
	v_lshlrev_b32_e32 v178, 16, v58
	v_and_b32_e32 v179, 0xffff0000, v58
	v_pk_add_f32 v[58:59], v[56:57], v[164:165]
	v_lshlrev_b32_e32 v174, 16, v60
	v_and_b32_e32 v175, 0xffff0000, v60
	v_pk_add_f32 v[60:61], v[58:59], v[162:163]
	v_lshlrev_b32_e32 v184, 16, v52
	v_and_b32_e32 v185, 0xffff0000, v52
	v_lshlrev_b32_e32 v194, 16, v53
	v_and_b32_e32 v195, 0xffff0000, v53
	v_exp_f32_e32 v52, v166
	v_exp_f32_e32 v53, v167
	v_exp_f32_e32 v56, v164
	v_exp_f32_e32 v57, v165
	v_exp_f32_e32 v58, v162
	v_exp_f32_e32 v59, v163
	v_pk_add_f32 v[162:163], v[60:61], v[160:161]
	v_lshlrev_b32_e32 v180, 16, v55
	v_and_b32_e32 v181, 0xffff0000, v55
	v_exp_f32_e32 v60, v160
	v_exp_f32_e32 v61, v161
	v_pk_add_f32 v[160:161], v[162:163], v[176:177]
	v_lshlrev_b32_e32 v196, 16, v54
	v_pk_add_f32 v[160:161], v[160:161], v[180:181]
	v_and_b32_e32 v197, 0xffff0000, v54
	v_exp_f32_e32 v176, v176
	v_exp_f32_e32 v177, v177
	v_pk_add_f32 v[160:161], v[160:161], v[184:185]
	v_exp_f32_e32 v180, v180
	v_exp_f32_e32 v181, v181
	v_pk_add_f32 v[198:199], v[160:161], v[196:197]
	v_pk_mul_f32 v[160:161], v[52:53], v[56:57]
	v_exp_f32_e32 v184, v184
	v_exp_f32_e32 v185, v185
	v_pk_mul_f32 v[170:171], v[160:161], v[170:171]
	v_pk_mul_f32 v[160:161], v[160:161], v[58:59]
	v_lshlrev_b32_e32 v164, 16, v159
	v_pk_mul_f32 v[172:173], v[160:161], v[172:173]
	v_pk_mul_f32 v[160:161], v[160:161], v[60:61]
	v_and_b32_e32 v165, 0xffff0000, v159
	v_pk_mul_f32 v[174:175], v[160:161], v[174:175]
	v_pk_mul_f32 v[160:161], v[160:161], v[176:177]
	v_and_b32_e32 v159, 0xffff, v62
	v_pk_mul_f32 v[178:179], v[160:161], v[178:179]
	v_pk_mul_f32 v[160:161], v[160:161], v[180:181]
	v_lshrrev_b32_e32 v62, 16, v62
	v_pk_mul_f32 v[182:183], v[160:161], v[182:183]
	v_pk_mul_f32 v[166:167], v[160:161], v[184:185]
	v_lshl_or_b32 v160, v63, 16, v159
	v_and_b32_e32 v159, 0xffff, v64
	v_lshl_or_b32 v161, v65, 16, v159
	v_and_b32_e32 v159, 0xffff, v66
	v_and_or_b32 v62, v63, s88, v62
	v_lshrrev_b32_e32 v63, 16, v64
	v_lshl_or_b32 v162, v67, 16, v159
	v_and_b32_e32 v159, 0xffff, v157
	v_and_or_b32 v63, v65, s88, v63
	v_lshrrev_b32_e32 v64, 16, v66
	v_lshrrev_b32_e32 v65, 16, v157
	v_exp_f32_e32 v196, v196
	v_exp_f32_e32 v197, v197
	v_lshl_or_b32 v163, v158, 16, v159
	v_and_or_b32 v64, v67, s88, v64
	v_and_or_b32 v65, v158, s88, v65
	v_add_u32_e32 v66, s75, v111
	ds_write_b64 v110, v[198:199]
	ds_write_b128 v66, v[160:163] offset:52224
	ds_write_b128 v66, v[62:65] offset:52368
	s_waitcnt lgkmcnt(0)
	s_barrier
	ds_read2st64_b64 v[64:67], v116 offset1:1
	ds_read2st64_b64 v[158:161], v116 offset0:2 offset1:3
	v_pk_mul_f32 v[62:63], v[166:167], v[196:197]
	v_pk_mul_f32 v[54:55], v[52:53], v[168:169]
	v_pk_mul_f32 v[200:201], v[62:63], v[164:165]
	ds_read2st64_b64 v[162:165], v116 offset0:4 offset1:5
	s_waitcnt lgkmcnt(2)
	v_add_f32_e32 v208, 0, v64
	v_pk_mul_f32 v[194:195], v[166:167], v[194:195]
	v_cndmask_b32_e64 v62, 0, v66, s[8:9]
	ds_read2st64_b64 v[166:169], v116 offset0:6 offset1:7
	v_cndmask_b32_e64 v64, 0, v208, s[6:7]
	s_waitcnt lgkmcnt(2)
	v_cndmask_b32_e64 v193, 0, v158, s[10:11]
	v_add_f32_e32 v62, v64, v62
	v_cndmask_b32_e64 v204, 0, v160, s[12:13]
	v_add_f32_e32 v62, v62, v193
	s_waitcnt lgkmcnt(1)
	v_cndmask_b32_e64 v209, 0, v162, s[14:15]
	v_add_f32_e32 v62, v62, v204
	v_cndmask_b32_e64 v211, 0, v164, s[16:17]
	v_add_f32_e32 v62, v62, v209
	s_waitcnt lgkmcnt(0)
	v_cndmask_b32_e64 v63, 0, v166, s[18:19]
	v_add_f32_e32 v209, v62, v211
	v_mov_b32_e32 v62, v66
	v_cndmask_b32_e64 v205, 0, v168, s[20:21]
	v_pk_add_f32 v[62:63], v[208:209], v[62:63]
	v_mov_b32_e32 v204, v158
	v_pk_add_f32 v[204:205], v[62:63], v[204:205]
	v_mov_b32_e32 v62, v160
	v_mov_b32_e32 v63, v198
	v_pk_add_f32 v[208:209], v[204:205], v[62:63]
	v_add_f32_e32 v64, 0, v65
	v_pk_add_f32 v[62:63], v[208:209], v[162:163]
	v_cndmask_b32_e64 v157, 0, v67, s[8:9]
	v_pk_add_f32 v[62:63], v[62:63], v[164:165]
	v_cndmask_b32_e64 v202, 0, v159, s[10:11]
	v_pk_add_f32 v[62:63], v[62:63], v[166:167]
	v_cndmask_b32_e64 v206, 0, v161, s[12:13]
	v_pk_add_f32 v[62:63], v[62:63], v[168:169]
	v_cndmask_b32_e64 v210, 0, v163, s[14:15]
	v_min_f32_e64 v63, -v208, s84
	v_exp_f32_e32 v66, v63
	v_sub_f32_e32 v63, v62, v208
	v_exp_f32_e32 v158, v63
	v_sub_f32_e32 v63, v208, v209
	v_min_f32_e32 v63, 0x42e60000, v63
	v_exp_f32_e32 v204, v63
	v_cndmask_b32_e64 v63, 0, v64, s[6:7]
	v_add_f32_e32 v63, v63, v157
	v_add_f32_e32 v63, v63, v202
	v_add_f32_e32 v63, v63, v206
	v_cndmask_b32_e64 v212, 0, v165, s[16:17]
	v_add_f32_e32 v63, v63, v210
	v_cndmask_b32_e64 v203, 0, v167, s[18:19]
	v_add_f32_e32 v65, v63, v212
	v_mov_b32_e32 v202, v67
	v_cndmask_b32_e64 v207, 0, v169, s[20:21]
	v_pk_add_f32 v[64:65], v[64:65], v[202:203]
	v_mov_b32_e32 v206, v159
	v_pk_add_f32 v[202:203], v[64:65], v[206:207]
	v_mov_b32_e32 v198, v161
	v_pk_add_f32 v[198:199], v[202:203], v[198:199]
	v_exp_f32_e32 v160, v205
	v_pk_add_f32 v[64:65], v[198:199], v[162:163] op_sel:[0,1] op_sel_hi:[1,0]
; #define LAS __attribute__((address_space(3)))
; __device__ __forceinline__ unsigned pkbf(float lo, float hi) { const f32x2_t v = {lo, hi}; const bf16x2_t b = __builtin_convertvector(v, bf16x2_t); return __builtin_bit_cast(unsigned, b); }
; __device__ __forceinline__ void hgrn_r3(const GAS bf16* proj, const GAS float* RU, const GAS float* RD, GAS bf16* y, int TOKG, const GAS float* ogain, unsigned char* lds, int tid, int lane, int wave, int bid, int G) {
;     ...
; #pragma unroll
;               for (int i = 7; i >= 0; --i) { const int s = wave * 8 + i;
;                   const float qh0 = qv0[i] * ep0, qh1 = qv1[i] * ep1;
;                   const float km0 = (1.f - f0[i]) * m0_, km1 = (1.f - f1[i]) * m1_;
;                   *(LAS unsigned*)(L + H3_QH + s * HQS + lane * 4) = pkbf(qh0, qh1);
;                   *(LAS unsigned*)(L + H3_QM + s * HQS + lane * 4) = pkbf(qh0 * eg0, qh1 * eg1);
;                   *(LAS unsigned*)(L + H3_KM + s * HQS + lane * 4) = pkbf(km0, km1);
;                   kv0[i] = km0 * tg0; kv1[i] = km1 * tg1; m0_ *= f0[i]; m1_ *= f1[i]; }
; #pragma unroll
;               for (int i = 0; i < 4; ++i) { kw0[i] = pkbf(kv0[2 * i], kv0[2 * i + 1]); kw1[i] = pkbf(kv1[2 * i], kv1[2 * i + 1]); }
;               { v4u a, b; a.x = kw0[0]; a.y = kw0[1]; a.z = kw0[2]; a.w = kw0[3]; b.x = kw1[0]; b.y = kw1[1]; b.z = kw1[2]; b.w = kw1[3];
;                 *(LAS v4u*)(L + H3_KT + (2 * lane) * HS + wave * 16) = a; *(LAS v4u*)(L + H3_KT + (2 * lane + 1) * HS + wave * 16) = b; }
;               if (wave == 0) *(LAS f32x2h*)(decl + 2 * lane) = (f32x2h){__builtin_amdgcn_exp2f(tot0), __builtin_amdgcn_exp2f(tot1)}; }
	v_min_f32_e64 v63, -v198, s84
	v_pk_add_f32 v[64:65], v[64:65], v[164:165] op_sel:[0,1] op_sel_hi:[1,0]
	v_exp_f32_e32 v161, v203
	v_pk_add_f32 v[64:65], v[64:65], v[166:167] op_sel:[0,1] op_sel_hi:[1,0]
	v_exp_f32_e32 v67, v63
	v_pk_add_f32 v[64:65], v[64:65], v[168:169] op_sel:[0,1] op_sel_hi:[1,0]
	v_pk_mul_f32 v[164:165], v[200:201], v[160:161]
	v_sub_f32_e32 v65, v198, v199
	v_min_f32_e32 v65, 0x42e60000, v65
	v_exp_f32_e32 v205, v65
	v_sub_f32_e32 v63, v64, v198
	v_exp_f32_e32 v162, v63
	v_cvt_pk_bf16_f32 v63, v164, v165
	v_pk_mul_f32 v[164:165], v[66:67], v[164:165]
	v_pk_add_f32 v[166:167], v[196:197], 1.0 op_sel_hi:[1,0] neg_lo:[1,0] neg_hi:[1,0]
	v_cvt_pk_bf16_f32 v65, v164, v165
	v_pk_mul_f32 v[164:165], v[194:195], v[160:161]
	v_pk_add_f32 v[168:169], v[184:185], 1.0 op_sel_hi:[1,0] neg_lo:[1,0] neg_hi:[1,0]
	v_pk_mul_f32 v[194:195], v[196:197], v[204:205]
	v_cvt_pk_bf16_f32 v159, v164, v165
	v_xor_b32_e32 v163, 16, v122
	v_add_u32_e32 v163, 0x400, v163
	v_pk_mul_f32 v[164:165], v[66:67], v[164:165]
	v_pk_mul_f32 v[166:167], v[166:167], v[204:205]
	v_pk_mul_f32 v[168:169], v[168:169], v[194:195]
	ds_write2_b32 v163, v159, v63 offset0:152 offset1:220
	v_cvt_pk_bf16_f32 v63, v164, v165
	v_xor_b32_e32 v159, 16, v122
	v_add_u32_e32 v159, 0x4800, v159
	v_cvt_pk_bf16_f32 v157, v166, v167
	ds_write2_b32 v159, v63, v65 offset0:152 offset1:220
	v_cvt_pk_bf16_f32 v63, v168, v169
	v_xor_b32_e32 v65, 16, v122
	v_add_u32_e32 v65, 0x8c00, v65
	v_mov_b32_e32 v164, v168
	v_mov_b32_e32 v165, v166
	v_mov_b32_e32 v166, v169
	v_pk_mul_f32 v[168:169], v[182:183], v[160:161]
	ds_write2_b32 v65, v63, v157 offset0:152 offset1:220
	v_cvt_pk_bf16_f32 v63, v168, v169
	v_pk_mul_f32 v[168:169], v[66:67], v[168:169]
	v_pk_add_f32 v[182:183], v[180:181], 1.0 op_sel_hi:[1,0] neg_lo:[1,0] neg_hi:[1,0]
	v_pk_mul_f32 v[184:185], v[184:185], v[194:195]
	v_cvt_pk_bf16_f32 v157, v168, v169
	v_pk_mul_f32 v[168:169], v[178:179], v[160:161]
	v_pk_mul_f32 v[182:183], v[182:183], v[184:185]
	v_pk_add_f32 v[178:179], v[176:177], 1.0 op_sel_hi:[1,0] neg_lo:[1,0] neg_hi:[1,0]
	v_pk_mul_f32 v[180:181], v[180:181], v[184:185]
	v_cvt_pk_bf16_f32 v184, v168, v169
	v_pk_mul_f32 v[168:169], v[66:67], v[168:169]
	v_pk_mul_f32 v[178:179], v[178:179], v[180:181]
	ds_write2_b32 v163, v184, v63 offset0:16 offset1:84
	v_cvt_pk_bf16_f32 v63, v168, v169
	v_cvt_pk_bf16_f32 v193, v182, v183
	ds_write2_b32 v159, v63, v157 offset0:16 offset1:84
	v_cvt_pk_bf16_f32 v63, v178, v179
	v_pk_mul_f32 v[174:175], v[174:175], v[160:161]
	ds_write2_b32 v65, v63, v193 offset0:16 offset1:84
	v_mov_b32_e32 v168, v178
	v_mov_b32_e32 v169, v182
	v_mov_b32_e32 v182, v179
	v_pk_mul_f32 v[176:177], v[176:177], v[180:181]
	v_cvt_pk_bf16_f32 v63, v174, v175
	v_pk_mul_f32 v[174:175], v[66:67], v[174:175]
	v_pk_mul_f32 v[172:173], v[172:173], v[160:161]
	v_pk_mul_f32 v[164:165], v[158:159], v[164:165] op_sel_hi:[0,1]
	v_pk_mul_f32 v[168:169], v[158:159], v[168:169] op_sel_hi:[0,1]
	v_pk_mul_f32 v[178:179], v[162:163], v[182:183] op_sel_hi:[0,1]
	v_pk_add_f32 v[182:183], v[60:61], 1.0 op_sel_hi:[1,0] neg_lo:[1,0] neg_hi:[1,0]
	v_cvt_pk_bf16_f32 v65, v174, v175
	v_pk_add_f32 v[174:175], v[58:59], 1.0 op_sel_hi:[1,0] neg_lo:[1,0] neg_hi:[1,0]
	v_pk_mul_f32 v[60:61], v[60:61], v[176:177]
	v_cvt_pk_bf16_f32 v159, v172, v173
	v_pk_mul_f32 v[172:173], v[66:67], v[172:173]
	v_pk_mul_f32 v[180:181], v[182:183], v[176:177]
	v_pk_mul_f32 v[174:175], v[174:175], v[60:61]
	ds_write2_b32 v122, v159, v63 offset0:136 offset1:204
	v_cvt_pk_bf16_f32 v63, v172, v173
	v_add_u32_e32 v159, 0x4400, v122
	v_pk_mul_f32 v[58:59], v[58:59], v[60:61]
	v_cvt_pk_bf16_f32 v157, v180, v181
	ds_write2_b32 v159, v63, v65 offset0:136 offset1:204
	v_cvt_pk_bf16_f32 v63, v174, v175
	v_add_u32_e32 v65, 0x8800, v122
	v_pk_mul_f32 v[170:171], v[170:171], v[160:161]
	v_pk_add_f32 v[176:177], v[56:57], 1.0 op_sel_hi:[1,0] neg_lo:[1,0] neg_hi:[1,0]
	v_pk_mul_f32 v[54:55], v[54:55], v[160:161]
	v_pk_add_f32 v[52:53], v[52:53], 1.0 op_sel_hi:[1,0] neg_lo:[1,0] neg_hi:[1,0]
	v_pk_mul_f32 v[56:57], v[56:57], v[58:59]
	ds_write2_b32 v65, v63, v157 offset0:136 offset1:204
	v_cvt_pk_bf16_f32 v63, v170, v171
	v_pk_mul_f32 v[170:171], v[66:67], v[170:171]
	v_pk_mul_f32 v[52:53], v[52:53], v[56:57]
	v_cvt_pk_bf16_f32 v56, v54, v55
	v_pk_mul_f32 v[54:55], v[66:67], v[54:55]
	v_mov_b32_e32 v173, v180
	v_mov_b32_e32 v180, v175
	v_pk_mul_f32 v[60:61], v[176:177], v[58:59]
	v_cvt_pk_bf16_f32 v157, v170, v171
	v_cvt_pk_bf16_f32 v54, v54, v55
	v_pk_mul_f32 v[166:167], v[162:163], v[166:167] op_sel_hi:[0,1]
	v_mov_b32_e32 v172, v174
	v_pk_mul_f32 v[174:175], v[162:163], v[180:181] op_sel_hi:[0,1]
	v_cvt_pk_bf16_f32 v163, v60, v61
	ds_write2_b32 v159, v54, v157 offset1:68
	v_cvt_pk_bf16_f32 v54, v52, v53
	ds_write2_b32 v65, v54, v163 offset1:68
	v_mov_b32_e32 v54, v52
	v_mov_b32_e32 v55, v60
	v_mov_b32_e32 v60, v53
	v_pk_mul_f32 v[172:173], v[158:159], v[172:173] op_sel_hi:[0,1]
	ds_write2_b32 v122, v56, v63 offset1:68
	v_pk_mul_f32 v[54:55], v[158:159], v[54:55] op_sel_hi:[0,1]
	v_pk_mul_f32 v[56:57], v[162:163], v[60:61] op_sel_hi:[0,1]
	v_cvt_pk_bf16_f32 v52, v54, v55
	v_cvt_pk_bf16_f32 v56, v56, v57
	v_cvt_pk_bf16_f32 v53, v172, v173
	v_cvt_pk_bf16_f32 v57, v174, v175
	v_cvt_pk_bf16_f32 v54, v168, v169
	v_cvt_pk_bf16_f32 v58, v178, v179
	v_cvt_pk_bf16_f32 v55, v164, v165
	v_cvt_pk_bf16_f32 v59, v166, v167
	s_andn2_b64 vcc, exec, s[70:71]
	ds_write_b128 v123, v[52:55]
	ds_write_b128 v124, v[56:59] offset:144
	s_cbranch_vccnz .LBB0_388
	v_exp_f32_e32 v52, v62
	v_exp_f32_e32 v53, v64
	ds_write_b64 v120, v[52:53]
